# v017 + attention QK: second score chain takes -m as C directly (8 v_mov_b64 removed) + work-queue id prefetch for attention and cross queues (next returning atomic issued at unit start, parked in v205
# speedup vs baseline: 1.0089x; 1.0081x over previous
; #define LAS __attribute__((address_space(3)))
; __global__ void __launch_bounds__(512, 2) fwd(Args args) {
;     ...
;         unsigned* qctr = (unsigned*)WS_(WS_CTL) + CW_QUEUE;
;         volatile LAS unsigned* qw = (volatile LAS unsigned*)(lds + LDSCTL_OFF + 64);
;         int qit = 0;
.LBB0_861:
	s_add_u32 s2, s50, 0x20200
	s_addc_u32 s3, s51, 0
	s_lshr_b32 s24, s63, 1
	s_add_u32 s25, s50, 0x70c00000
	s_addc_u32 s26, s51, 0
	s_lshl_b32 s0, s33, 1
	s_or_b32 s27, s0, 1
	s_and_b32 s4, s0, 2
	v_readlane_b32 s0, v255, 22
	s_ashr_i32 s5, s0, 7
	s_lshl_b32 s0, s5, 5
	s_lshl_b32 s12, s33, 4
	s_lshl_b32 s33, s33, 11
	s_lshl_b32 s16, s27, 3
	s_lshl_b32 s38, s27, 10
	s_ashr_i32 s1, s0, 31
	s_ashr_i32 s13, s12, 31
	s_add_i32 s37, s33, 0
	s_ashr_i32 s17, s16, 31
	s_add_i32 s39, s38, 0
	s_lshl_b64 s[0:1], s[0:1], 1
	s_add_u32 s0, s50, s0
	s_addc_u32 s1, s51, s1
	s_add_u32 s28, s0, 0x74c00000
	s_addc_u32 s29, s1, 0
	s_lshl_b32 s30, s5, 12
	s_lshl_b32 s31, s4, 4
	s_lshl_b32 s34, s4, 10
	s_or_b32 s4, s4, 1
	s_add_i32 s0, s30, 0
	s_lshl_b32 s43, s4, 10
	s_add_i32 s1, s0, s34
	s_lshl_b32 s42, s4, 4
	s_add_i32 s0, s0, s43
	s_mov_b64 s[4:5], s[48:49]
	s_add_i32 s44, s0, 0x4000
	s_mov_b64 s[6:7], s[50:51]
	s_add_i32 s48, s0, 0xc000
	s_lshl_b32 s41, s84, 13
	s_lshl_b32 s0, s63, 14
	s_add_i32 s35, s1, 0x4000
	s_add_i32 s45, s37, 0x8000
	s_add_i32 s46, s39, 0x8000
	s_add_i32 s47, s1, 0xc000
	s_add_i32 s40, s85, 0x20400
	s_add_i32 s49, s41, 0
	s_add_i32 s50, s0, 0
	s_add_u32 s51, s6, 0x64900000
	s_addc_u32 s52, s7, 0
	s_or_b32 s53, s31, 0x90
	s_or_b32 s54, s31, 0x80
	s_add_u32 s55, s6, 0x70c08000
	s_mov_b32 s15, 0
	s_addc_u32 s56, s7, 0
	v_mov_b32_e32 v195, 0
	s_movk_i32 s57, 0x5800
	s_mov_b64 s[18:19], 0x4000
	v_mov_b32_e32 v211, 0x3727c5ac
	s_mov_b32 s58, 0xf800000
	v_mov_b32_e32 v212, 0x260
	s_mov_b32 s59, 0x3f4ccccd
	s_mov_b64 s[20:21], 0x1800
	s_movk_i32 s60, 0x1000
	s_movk_i32 s61, 0x7fff
	s_movk_i32 s62, 0x1800
	v_mov_b32_e32 v213, 0x5800
	s_and_saveexec_b64 s[0:1], s[82:83]
	s_cbranch_execz .Lattn_q_pre
	s_waitcnt vmcnt(0)
	v_mov_b32_e32 v205, 1
	s_nop 0
	global_atomic_add v205, v195, v205, s[2:3] sc0
.Lattn_q_pre:
	s_or_b64 exec, exec, s[0:1]
	s_branch .LBB0_864

; DI int tid_now() { int t; asm volatile("v_mov_b32 %0, %1" : "=v"(t) : "v"((int)threadIdx.x)); return t; }
; #define Q_NEXT(k, id) do { if (tid == 0) qw[qit & 1] = __hip_atomic_fetch_add(qctr + 64 * (k), 1u, __ATOMIC_RELAXED, __HIP_MEMORY_SCOPE_AGENT); __syncthreads(); \
;         id = __builtin_amdgcn_readfirstlane((int)qw[qit & 1]); ++qit; } while (0)
; __global__ void __launch_bounds__(512, 2) fwd(Args args) {
;     ...
;         for (;;) { int id; Q_NEXT(2, id); if (id >= 2048) break; const int lane = tid_now() & 63; fa::attn_unit(A_, lds, id >> 8, (id >> 5) & 7, 31 - (id & 31), lam, wave, lane); }
.LBB0_864:
	s_and_b32 s8, s36, 1
	s_and_saveexec_b64 s[0:1], s[82:83]
	s_cbranch_execz .LBB0_868
	s_mov_b64 s[6:7], exec
	v_mbcnt_lo_u32_b32 v2, s6, 0
	v_mbcnt_hi_u32_b32 v2, s7, v2
	v_cmp_eq_u32_e32 vcc, 0, v2
	s_and_saveexec_b64 s[4:5], vcc
	s_cbranch_execz .LBB0_867
	s_waitcnt vmcnt(0)
	v_mov_b32_e32 v3, v205
	v_mov_b32_e32 v205, 1
	s_nop 0
	global_atomic_add v205, v195, v205, s[2:3] sc0
.LBB0_867:
	s_or_b64 exec, exec, s[4:5]
	s_lshl_b32 s4, s8, 2
	s_add_i32 s4, s4, 0
	s_add_i32 s4, s4, 0x20040
	v_readfirstlane_b32 s5, v3
	v_mov_b32_e32 v3, s4
	s_nop 0
	v_add_u32_e32 v2, s5, v2
	ds_write_b32 v3, v2

; #define LAS __attribute__((address_space(3)))
; #define LOADV(f, ks) _Pragma("unroll") for (int nb = 0; nb < 4; ++nb) { const s16x4 lo = vtr(vp + nb * 4096 + (ks) * 1024), hi = vtr(vp + nb * 4096 + (ks) * 1024 + 512); f[nb] = __builtin_shufflevector(lo, hi, 0, 1, 2, 3, 4, 5, 6, 7); }
; #define MX3(a, b, c) __builtin_fmaxf(__builtin_fmaxf((a), (b)), (c))
; DI void attn_unit(Ctx A_, LAS unsigned char* lds, int b, int h, int qb, float lam, int wave, int lane) {
;     ...
;             { bf16x8 kf[8];
;               if (first) {
; #pragma unroll
;                   for (int d0 = 0; d0 < 2; ++d0) { kfa[2 * d0] = *(const LAS bf16x8*)(kb + d0 * 2048); kfa[2 * d0 + 1] = *(const LAS bf16x8*)(kb + d0 * 2048 + 512); }
;               }
; #pragma unroll
;               for (int d0 = 2; d0 < 4; ++d0) { kf[2 * d0] = *(const LAS bf16x8*)(kb + d0 * 2048); kf[2 * d0 + 1] = *(const LAS bf16x8*)(kb + d0 * 2048 + 512); }
; #pragma unroll
;               for (int i = 0; i < 4; ++i) kf[i] = kfa[i];
;               LOADV(fa4, 0) LOADV(fb4, 1)
;               __builtin_amdgcn_sched_barrier(0);
;               __builtin_amdgcn_s_setprio(1);
; #pragma unroll
;               for (int d0 = 0; d0 < 4; ++d0) {
;                   p0 = __builtin_amdgcn_mfma_f32_32x32x16_bf16(kf[2 * d0], qr[d0], d0 == 0 ? negm : p0, 0, 0, 0);
;                   p1 = __builtin_amdgcn_mfma_f32_32x32x16_bf16(kf[2 * d0 + 1], qr[d0], d0 == 0 ? negm : p1, 0, 0, 0);
;               }
;               __builtin_amdgcn_s_setprio(0);
;               __builtin_amdgcn_sched_barrier(0); }
;     ...
;             float ta = MX3(p0[0], p0[1], p1[0]), tb2 = MX3(p0[2], p0[3], p1[1]); ta = MX3(ta, p1[2], p1[3]);
; #pragma unroll
;             for (int i = 4; i < 16; i += 4) { ta = MX3(ta, p0[i], p0[i + 1]); tb2 = MX3(tb2, p0[i + 2], p0[i + 3]); ta = MX3(ta, p1[i], p1[i + 1]); tb2 = MX3(tb2, p1[i + 2], p1[i + 3]); }
;     ...
;             float tm = fmaxf(ta, tb2);
;             { const auto rr = __builtin_amdgcn_permlane32_swap(__float_as_uint(tm), __float_as_uint(tm), false, false); tm = fmaxf(__uint_as_float(rr[0]), __uint_as_float(rr[1])); }
;             const bool resc = first || __any(tm > RESC_THR);
.LBB0_880:
	ds_read_b128 v[222:225], v82 offset:4096
	ds_read_b128 v[226:229], v82 offset:4608
	ds_read_b128 v[230:233], v82 offset:6144
	ds_read_b128 v[234:237], v82 offset:6656
	ds_read_b64_tr_b16 v[134:135], v220 offset:16384
	ds_read_b64_tr_b16 v[136:137], v220 offset:16896
	ds_read_b64_tr_b16 v[126:127], v220 offset:17408
	ds_read_b64_tr_b16 v[128:129], v220 offset:17920
	ds_read_b64_tr_b16 v[142:143], v220 offset:20480
	ds_read_b64_tr_b16 v[144:145], v220 offset:20992
	ds_read_b64_tr_b16 v[122:123], v220 offset:21504
	ds_read_b64_tr_b16 v[124:125], v220 offset:22016
	ds_read_b64_tr_b16 v[138:139], v220 offset:24576
	ds_read_b64_tr_b16 v[140:141], v220 offset:25088
	ds_read_b64_tr_b16 v[118:119], v220 offset:25600
	ds_read_b64_tr_b16 v[120:121], v220 offset:26112
	ds_read_b64_tr_b16 v[130:131], v220 offset:28672
	ds_read_b64_tr_b16 v[132:133], v220 offset:29184
	ds_read_b64_tr_b16 v[114:115], v220 offset:29696
	ds_read_b64_tr_b16 v[116:117], v220 offset:30208
	s_setprio 1
	s_waitcnt lgkmcnt(14)
	v_mfma_f32_32x32x16_bf16 v[98:113], v[174:177], v[158:161], v[66:81]
	v_mfma_f32_32x32x16_bf16 v[82:97], v[178:181], v[158:161], v[66:81]
	v_mfma_f32_32x32x16_bf16 v[98:113], v[182:185], v[154:157], v[98:113]
	v_mfma_f32_32x32x16_bf16 v[82:97], v[186:189], v[154:157], v[82:97]
	v_mfma_f32_32x32x16_bf16 v[98:113], v[222:225], v[150:153], v[98:113]
	v_mfma_f32_32x32x16_bf16 v[82:97], v[226:229], v[150:153], v[82:97]
	v_mfma_f32_32x32x16_bf16 v[98:113], v[230:233], v[146:149], v[98:113]
	v_mfma_f32_32x32x16_bf16 v[82:97], v[234:237], v[146:149], v[82:97]
	s_setprio 0
	s_nop 9
	v_max_f32_e32 v174, v99, v99
	v_max_f32_e32 v175, v98, v98
	v_max_f32_e32 v174, v175, v174
	v_max3_f32 v175, v100, v101, v83
	v_max3_f32 v174, v174, v82, v84
	v_max3_f32 v174, v174, v85, v102
	v_max3_f32 v175, v175, v104, v105
	v_max3_f32 v174, v174, v103, v86
	v_max3_f32 v175, v175, v88, v89
	v_max3_f32 v174, v174, v87, v106
	v_max3_f32 v175, v175, v108, v109
	v_max3_f32 v174, v174, v107, v90
	v_max3_f32 v175, v175, v92, v93
	v_max3_f32 v174, v174, v91, v110
	v_max3_f32 v175, v175, v112, v113
	v_max3_f32 v174, v174, v111, v94
	v_max3_f32 v175, v175, v96, v97
	v_max3_f32 v174, v174, v95, v175
	v_mov_b32_e32 v175, v174
	s_nop 1
	v_permlane32_swap_b32_e32 v174, v175
	v_max_f32_e32 v175, v175, v175
	v_max_f32_e32 v174, v174, v174
	v_max_f32_e32 v174, v174, v175
	s_andn2_b64 vcc, exec, s[6:7]
	s_mov_b64 s[22:23], -1
	s_cbranch_vccnz .LBB0_882
	s_mov_b32 s6, 0x41000000
	v_cmp_lt_f32_e32 vcc, s6, v174
	s_cmp_lg_u64 vcc, 0
	s_cselect_b64 s[22:23], -1, 0

; DI int tid_now() { int t; asm volatile("v_mov_b32 %0, %1" : "=v"(t) : "v"((int)threadIdx.x)); return t; }
; #define PROBE_T0(k) unsigned long long pt0_ = 0; if ((k) == PROBE_PH) pt0_ = __builtin_amdgcn_s_memrealtime();
; #define Q_NEXT(k, id) do { if (tid == 0) qw[qit & 1] = __hip_atomic_fetch_add(qctr + 64 * (k), 1u, __ATOMIC_RELAXED, __HIP_MEMORY_SCOPE_AGENT); __syncthreads(); \
;         id = __builtin_amdgcn_readfirstlane((int)qw[qit & 1]); ++qit; } while (0)
; __global__ void __launch_bounds__(512, 2) fwd(Args args) {
;     ...
;         { PROBE_T0(23)
; #pragma unroll 1
;         for (;;) { int id; Q_NEXT(3, id); if (id >= 1152) break; const int lane = tid_now() & 63;
.LBB0_896:
	v_readlane_b32 s12, v254, 60
	v_readlane_b32 s14, v254, 62
	v_readlane_b32 s15, v254, 63
	s_add_u32 s0, s14, 0x20300
	s_addc_u32 s1, s15, 0
	s_add_u32 s42, s14, 0x17600000
	s_addc_u32 s43, s15, 0
	s_and_b32 s44, s80, 0x60
	s_lshl_b32 s45, s27, 4
	s_bfe_i64 s[4:5], s[80:81], 0x200000
	s_add_i32 s47, s37, 0x4000
	s_add_i32 s48, s37, 0x4400
	s_cmp_eq_u32 s44, 0
	s_cselect_b64 s[6:7], -1, 0
	s_lshl_b32 s8, s84, 7
	s_ashr_i32 s9, s8, 31
	s_lshl_b64 s[8:9], s[8:9], 1
	v_readlane_b32 s10, v255, 9
	v_readlane_b32 s11, v255, 10
	s_add_u32 s49, s10, s8
	s_addc_u32 s50, s11, s9
	s_add_u32 s51, s14, s8
	s_addc_u32 s52, s15, s9
	s_add_u32 s53, s51, 0x64901000
	s_addc_u32 s54, s52, 0
	s_lshl_b64 s[8:9], s[4:5], 1
	s_add_u32 s2, s14, s8
	s_addc_u32 s4, s15, s9
	s_add_u32 s10, s2, 0x17e20800
	s_addc_u32 s11, s4, 0
	s_add_u32 s55, s14, 0x17e20000
	s_addc_u32 s56, s15, 0
	v_readlane_b32 s13, v254, 61
	s_add_u32 s12, s2, 0x17620800
	s_addc_u32 s13, s4, 0
	s_add_u32 s57, s14, 0x17620000
	s_movk_i32 s46, 0x4000
	s_mov_b32 s3, 0
	s_addc_u32 s58, s15, 0
	v_mov_b32_e32 v3, 0
	s_mov_b64 s[14:15], 0x800
	s_mov_b64 s[16:17], 0x10800
	s_movk_i32 s59, 0x5800
	s_mov_b64 s[18:19], 0x4800
	s_mov_b64 s[20:21], 0x10000
	s_mov_b64 s[22:23], 0x20000
	s_movk_i32 s60, 0x5000
	s_movk_i32 s61, 0x7fff
	s_movk_i32 s62, 0x1800
	s_mov_b64 s[24:25], 0x64901040
	s_mov_b64 s[26:27], 0x64901080
	s_mov_b64 s[28:29], 0x649010c0
	s_waitcnt vmcnt(2)
	v_mov_b32_e32 v165, 0x5800
	s_and_saveexec_b64 s[4:5], s[82:83]
	s_cbranch_execz .Lcross_q_pre
	s_waitcnt vmcnt(0)
	v_mov_b32_e32 v205, 1
	s_nop 0
	global_atomic_add v205, v3, v205, s[0:1] sc0
.Lcross_q_pre:
	s_or_b64 exec, exec, s[4:5]
	s_branch .LBB0_900

; DI int tid_now() { int t; asm volatile("v_mov_b32 %0, %1" : "=v"(t) : "v"((int)threadIdx.x)); return t; }
; #define Q_NEXT(k, id) do { if (tid == 0) qw[qit & 1] = __hip_atomic_fetch_add(qctr + 64 * (k), 1u, __ATOMIC_RELAXED, __HIP_MEMORY_SCOPE_AGENT); __syncthreads(); \
;         id = __builtin_amdgcn_readfirstlane((int)qw[qit & 1]); ++qit; } while (0)
; __global__ void __launch_bounds__(512, 2) fwd(Args args) {
;     ...
;         for (;;) { int id; Q_NEXT(3, id); if (id >= 1152) break; const int lane = tid_now() & 63;
.LBB0_900:
	s_and_b32 s2, s36, 1
	s_and_saveexec_b64 s[4:5], s[82:83]
	s_cbranch_execz .LBB0_904
	s_mov_b64 s[34:35], exec
	v_mbcnt_lo_u32_b32 v2, s34, 0
	v_mbcnt_hi_u32_b32 v2, s35, v2
	v_cmp_eq_u32_e32 vcc, 0, v2
	s_and_saveexec_b64 s[30:31], vcc
	s_cbranch_execz .LBB0_903
	s_waitcnt vmcnt(0)
	v_mov_b32_e32 v4, v205
	v_mov_b32_e32 v205, 1
	s_nop 0
	global_atomic_add v205, v3, v205, s[0:1] sc0
.LBB0_903:
	s_or_b64 exec, exec, s[30:31]
	s_lshl_b32 s30, s2, 2
	s_add_i32 s30, s30, 0
	s_add_i32 s30, s30, 0x20040
	v_readfirstlane_b32 s31, v4
	v_mov_b32_e32 v4, s30
	s_nop 0
	v_add_u32_e32 v2, s31, v2
	ds_write_b32 v4, v2
